# combo3: combo2 + up-projection epilogue: next-unit row statistic load kept raw in v252-253, converted at the tail behind a counted vmcnt(16) (no store drain)
# speedup vs baseline: 1.0029x; 1.0029x over previous
; __device__ __forceinline__ float rsq_sum(const u64_t* rsq, int row) { return (float)rsq[row] * (1.0f / 16777216.0f); }
; __device__ __forceinline__ float row_rstd(const u64_t* rsq, int row) { return fast_rsq(rsq_sum(rsq, row) * (1.0f / DM) + EPS); }
; #define PG8_EPI_BAR() do { asm volatile("s_waitcnt lgkmcnt(0)" ::: "memory"); __builtin_amdgcn_s_barrier(); asm volatile("" ::: "memory"); } while (0)
;     __device__ __forceinline__ void run(const f32x4 (&acc)[2][2][4][2], const Unit& u, const Unit& nxt, bool has_next, int ui, int wr, int wc, int fr_in, int fq_in) const {
;         int fr = fr_in, fq = fq_in; asm volatile("" : "+v"(fr), "+v"(fq));
;         const int tid = (wr * 4 + wc) * 64 + fq * 16 + fr;
;         const int slot = ui & 1;
;         if (ui == 0) {
;             prm[slot * 1024 + tid] = ldp(tid, u.pn); prm[slot * 1024 + tid + 512] = ldp(tid + 512, u.pn);
;             if (tid < 256) rsd[slot * 256 + tid] = row_rstd(rsq, u.pm * BM + tid);
;             PG8_EPI_BAR();
;         }
;         float nx0 = 0.f, nx1 = 0.f, nrs = 1.f;
;         if (has_next) { nx0 = ldp(tid, nxt.pn); nx1 = ldp(tid + 512, nxt.pn); if (tid < 256) nrs = rsq_sum(rsq, nxt.pm * BM + tid); }
.LBB0_690:
	v_bfe_u32 v73, v226, 7, 2
	v_ashrrev_i32_e32 v72, 9, v226
	v_and_b32_e32 v74, 0x7f, v226
	v_mul_u32_u24_e32 v75, 0x1600, v73
	v_cmp_eq_u32_e32 vcc, 3, v73
	v_add_u32_e32 v102, 0x200, v226
	v_mul_i32_i24_e32 v72, 0xb00, v72
	v_cndmask_b32_e64 v100, v75, 0, vcc
	v_lshl_or_b32 v101, s34, 7, v74
	v_mov_b32_e32 v73, s7
	v_mov_b32_e32 v74, s9
	v_ashrrev_i32_e32 v102, 9, v102
	v_add3_u32 v72, v101, v72, v100
	v_cndmask_b32_e32 v75, v73, v74, vcc
	v_mov_b32_e32 v73, s6
	v_mov_b32_e32 v74, s8
	v_mul_i32_i24_e32 v102, 0xb00, v102
	v_cndmask_b32_e32 v74, v73, v74, vcc
	v_ashrrev_i32_e32 v73, 31, v72
	v_add3_u32 v100, v102, v101, v100
	v_lshl_add_u64 v[72:73], v[72:73], 2, v[74:75]
	v_ashrrev_i32_e32 v101, 31, v100
	v_lshl_add_u64 v[74:75], v[100:101], 2, v[74:75]
	global_load_dword v228, v[72:73], off
	global_load_dword v227, v[74:75], off
	v_cmp_gt_i32_e32 vcc, s65, v226
	v_mov_b32_e32 v229, 0x3a80218e
	s_and_saveexec_b64 s[0:1], vcc
	s_cbranch_execz .LBB0_692
	v_lshl_add_u32 v72, s36, 8, v226
	v_ashrrev_i32_e32 v73, 31, v72
	v_lshl_add_u64 v[72:73], v[72:73], 3, s[22:23]
	global_load_dwordx2 v[252:253], v[72:73], off

; __device__ __forceinline__ unsigned pk2(float lo, float hi) { f32x2_t v = {lo, hi}; bf16x2_t b = __builtin_convertvector(v, bf16x2_t); return __builtin_bit_cast(unsigned, b); }
; __device__ __forceinline__ float sigmoidf_(float v) { return fast_rcp(1.0f + fast_exp2(-v * LOG2E)); }
;     __device__ __forceinline__ void run(const f32x4 (&acc)[2][2][4][2], const Unit& u, const Unit& nxt, bool has_next, int ui, int wr, int wc, int fr_in, int fq_in) const {
;     ...
;             for (int ai = 0; ai < 2; ++ai) {
;                 const int grp = 2 * ai + wr;
;                 f32x4 hg2 = {0.f, 0.f, 0.f, 0.f}, hg3 = hg2, hv2 = hg2, hv3 = hg2;
;                 if (grp > 0 && fr == 0) { const PG8_LAS float* xp = xr + ((grp - 1) * 2) * 256 + cl;
;                     hg2 = *(const PG8_LAS f32x4*)(xp); hg3 = *(const PG8_LAS f32x4*)(xp + 256); hv2 = *(const PG8_LAS f32x4*)(xp + 128); hv3 = *(const PG8_LAS f32x4*)(xp + 256 + 128); }
;                 f32x4 pg2, pg1, pv2, pv1;
;                 {
;                     const f32x4 g2 = acc[ai][0][2][n] * rs[ai][2], g3 = acc[ai][0][3][n] * rs[ai][3], v2 = acc[ai][1][2][n] * rs[ai][2], v3 = acc[ai][1][3][n] * rs[ai][3];
; #pragma unroll
;                     for (int i = 0; i < 4; ++i) {
;                         float a0 = g2[i], a1 = g3[i], a2 = v2[i], a3 = v3[i];
;                         asm volatile("" : "+v"(a0), "+v"(a1), "+v"(a2), "+v"(a3));
;                         const float t0 = DPPF(a0, 0x111), t1 = DPPF(a1, 0x111), t2 = DPPF(a2, 0x111), t3 = DPPF(a3, 0x111);
;                         pg2[i] = t0 + hg2[i]; pg1[i] = t1 + hg3[i]; pv2[i] = t2 + hv2[i]; pv1[i] = t3 + hv3[i]; }
;                 }
; #pragma unroll
;                 for (int m = 0; m < 4; ++m) {
;                     const f32x4 gc = acc[ai][0][m][n] * rs[ai][m], vc = acc[ai][1][m][n] * rs[ai][m];
;                     const f32x4 cgt = bg + wg0 * pg2 + wg1 * pg1 + wg2 * gc, cvl = bv + wv0 * pv2 + wv1 * pv1 + wv2 * vc;
;                     float a[4];
; #pragma unroll
;                     for (int i = 0; i < 4; ++i) a[i] = cgt[i] * sigmoidf_(cgt[i]) * cvl[i];
;                     u32x2 w; w.x = pk2(a[0], a[1]); w.y = pk2(a[2], a[3]);
;                     *(u32x2*)(A + (size_t)(u.pm * BM + ai * 128 + wr * 64 + 4 * fr + m) * DFF + ch) = w;
;                     pg2 = pg1; pg1 = gc; pv2 = pv1; pv1 = vc;
;                 }
.LBB0_725:
	s_or_b64 exec, exec, s[0:1]
	v_mul_f32_e32 v53, v12, v74
	v_mul_f32_e32 v55, v4, v75
	v_mul_f32_e32 v59, v8, v74
	v_mul_f32_e32 v61, v0, v75
	v_mov_b32_e32 v54, 0
	v_mov_b32_e32 v58, 0
	v_mov_b32_e32 v60, 0
	v_mov_b32_e32 v52, 0
	v_mov_b32_dpp v54, v55 row_shr:1 row_mask:0xf bank_mask:0xf
	v_mov_b32_dpp v58, v59 row_shr:1 row_mask:0xf bank_mask:0xf
	v_mov_b32_dpp v60, v61 row_shr:1 row_mask:0xf bank_mask:0xf
	v_mul_f32_e32 v55, v13, v74
	v_mul_f32_e32 v59, v5, v75
	v_mul_f32_e32 v61, v9, v74
	v_mul_f32_e32 v62, v1, v75
	v_mov_b32_dpp v52, v53 row_shr:1 row_mask:0xf bank_mask:0xf
	v_mov_b32_e32 v53, 0
	v_mov_b32_e32 v48, v72
	v_mov_b32_e32 v49, v72
	v_mov_b32_dpp v53, v55 row_shr:1 row_mask:0xf bank_mask:0xf
	v_mov_b32_e32 v55, 0
	s_waitcnt lgkmcnt(0)
	v_pk_add_f32 v[40:41], v[40:41], v[52:53]
	v_pk_mul_f32 v[28:29], v[28:29], v[48:49]
	v_mov_b32_dpp v55, v59 row_shr:1 row_mask:0xf bank_mask:0xf
	v_pk_add_f32 v[36:37], v[36:37], v[54:55]
	v_pk_fma_f32 v[40:41], v[84:85], v[40:41], v[96:97]
	v_mov_b32_e32 v59, 0
	v_pk_fma_f32 v[40:41], v[88:89], v[36:37], v[40:41]
	v_mul_f32_e32 v63, v14, v74
	v_pk_fma_f32 v[40:41], v[28:29], v[92:93], v[40:41]
	v_mul_f32_e32 v101, v6, v75
	v_mul_f32_e32 v103, v10, v74
	v_mul_f32_e32 v109, v2, v75
	v_mul_f32_e32 v52, 0xbfb8aa3b, v40
	v_mul_f32_e32 v53, 0xbfb8aa3b, v41
	v_mov_b32_dpp v59, v61 row_shr:1 row_mask:0xf bank_mask:0xf
	v_mov_b32_e32 v61, 0
	v_mov_b32_e32 v100, 0
	v_mov_b32_e32 v102, 0
	v_mov_b32_e32 v108, 0
	v_exp_f32_e32 v52, v52
	v_exp_f32_e32 v53, v53
	v_mov_b32_dpp v61, v62 row_shr:1 row_mask:0xf bank_mask:0xf
	v_mov_b32_e32 v62, 0
	v_mov_b32_dpp v100, v101 row_shr:1 row_mask:0xf bank_mask:0xf
	v_mov_b32_dpp v102, v103 row_shr:1 row_mask:0xf bank_mask:0xf
	v_mov_b32_dpp v108, v109 row_shr:1 row_mask:0xf bank_mask:0xf
	v_mul_f32_e32 v101, v15, v74
	v_mul_f32_e32 v103, v7, v75
	v_mul_f32_e32 v109, v11, v74
	v_mul_f32_e32 v110, v3, v75
	v_mov_b32_dpp v62, v63 row_shr:1 row_mask:0xf bank_mask:0xf
	v_mov_b32_e32 v63, 0
	v_add_f32_e32 v52, 1.0, v52
	v_add_f32_e32 v53, 1.0, v53
	v_mov_b32_dpp v63, v101 row_shr:1 row_mask:0xf bank_mask:0xf
	v_mov_b32_e32 v101, 0
	v_rcp_f32_e32 v52, v52
	v_rcp_f32_e32 v53, v53
	v_mov_b32_dpp v101, v103 row_shr:1 row_mask:0xf bank_mask:0xf
	v_mov_b32_e32 v103, 0
	v_pk_add_f32 v[42:43], v[42:43], v[62:63]
	v_mov_b32_e32 v111, v72
	v_mov_b32_dpp v103, v109 row_shr:1 row_mask:0xf bank_mask:0xf
	v_mov_b32_e32 v109, 0
	v_pk_add_f32 v[38:39], v[38:39], v[100:101]
	v_pk_fma_f32 v[42:43], v[86:87], v[42:43], v[98:99]
	v_mov_b32_dpp v109, v110 row_shr:1 row_mask:0xf bank_mask:0xf
	v_mov_b32_e32 v110, v72
	v_pk_mul_f32 v[30:31], v[30:31], v[110:111]
	v_pk_fma_f32 v[42:43], v[90:91], v[38:39], v[42:43]
	v_pk_mul_f32 v[40:41], v[40:41], v[52:53]
	v_pk_fma_f32 v[42:43], v[30:31], v[94:95], v[42:43]
	v_pk_add_f32 v[32:33], v[32:33], v[58:59]
	v_mul_f32_e32 v52, 0xbfb8aa3b, v42
	v_mul_f32_e32 v53, 0xbfb8aa3b, v43
	v_exp_f32_e32 v52, v52
	v_exp_f32_e32 v53, v53
	v_pk_mul_f32 v[24:25], v[24:25], v[48:49]
	v_pk_add_f32 v[48:49], v[104:105], v[60:61]
	v_pk_fma_f32 v[32:33], v[64:65], v[32:33], v[80:81]
	v_add_f32_e32 v52, 1.0, v52
	v_add_f32_e32 v53, 1.0, v53
	v_pk_fma_f32 v[32:33], v[68:69], v[48:49], v[32:33]
	v_rcp_f32_e32 v52, v52
	v_rcp_f32_e32 v53, v53
	v_pk_fma_f32 v[32:33], v[24:25], v[76:77], v[32:33]
	v_pk_add_f32 v[34:35], v[34:35], v[102:103]
	v_pk_mul_f32 v[32:33], v[32:33], v[40:41]
	v_pk_add_f32 v[40:41], v[106:107], v[108:109]
	v_pk_fma_f32 v[34:35], v[66:67], v[34:35], v[82:83]
	v_pk_mul_f32 v[26:27], v[26:27], v[110:111]
	v_pk_fma_f32 v[34:35], v[70:71], v[40:41], v[34:35]
	v_pk_mul_f32 v[42:43], v[42:43], v[52:53]
	v_pk_fma_f32 v[34:35], v[26:27], v[78:79], v[34:35]
	v_cvt_pk_bf16_f32 v32, v32, v33
	v_pk_mul_f32 v[34:35], v[34:35], v[42:43]
	v_mov_b32_e32 v50, v73
	v_cvt_pk_bf16_f32 v33, v34, v35
	v_lshl_add_u64 v[34:35], v[122:123], 0, v[56:57]
	v_mov_b32_e32 v51, v73
	global_store_dwordx2 v[34:35], v[32:33], off
	v_pk_fma_f32 v[32:33], v[84:85], v[36:37], v[96:97]
	v_pk_mul_f32 v[20:21], v[20:21], v[50:51]
	v_pk_fma_f32 v[32:33], v[28:29], v[88:89], v[32:33]
	v_mov_b32_e32 v72, v73
	v_pk_fma_f32 v[32:33], v[20:21], v[92:93], v[32:33]
	v_pk_mul_f32 v[22:23], v[22:23], v[72:73]
	v_mul_f32_e32 v34, 0xbfb8aa3b, v32
	v_mul_f32_e32 v35, 0xbfb8aa3b, v33
	v_exp_f32_e32 v34, v34
	v_exp_f32_e32 v35, v35
	v_mov_b32_e32 v46, v74
	v_mov_b32_e32 v47, v74
	v_add_f32_e32 v34, 1.0, v34
	v_add_f32_e32 v35, 1.0, v35
	v_rcp_f32_e32 v34, v34
	v_rcp_f32_e32 v35, v35
	v_pk_fma_f32 v[28:29], v[28:29], v[84:85], v[96:97]
	v_mov_b32_e32 v44, v75
	v_mov_b32_e32 v45, v75
	v_pk_mul_f32 v[32:33], v[32:33], v[34:35]
	v_pk_fma_f32 v[34:35], v[86:87], v[38:39], v[98:99]
	v_pk_mul_f32 v[12:13], v[12:13], v[46:47]
	v_pk_fma_f32 v[34:35], v[30:31], v[90:91], v[34:35]
; __device__ __forceinline__ unsigned pk2(float lo, float hi) { f32x2_t v = {lo, hi}; bf16x2_t b = __builtin_convertvector(v, bf16x2_t); return __builtin_bit_cast(unsigned, b); }
; __device__ __forceinline__ float fast_rsq(float x) { return __builtin_amdgcn_rsqf(x); }
;     __device__ __forceinline__ void run(const f32x4 (&acc)[2][2][4][2], const Unit& u, const Unit& nxt, bool has_next, int ui, int wr, int wc, int fr_in, int fq_in) const {
;     ...
;                     u32x2 w; w.x = pk2(a[0], a[1]); w.y = pk2(a[2], a[3]);
;                     *(u32x2*)(A + (size_t)(u.pm * BM + ai * 128 + wr * 64 + 4 * fr + m) * DFF + ch) = w;
;                     pg2 = pg1; pg1 = gc; pv2 = pv1; pv1 = vc;
;                 }
;                 asm volatile("" ::: "memory");
;             }
;         }
;         if (has_next) {
;             prm[(slot ^ 1) * 1024 + tid] = nx0; prm[(slot ^ 1) * 1024 + tid + 512] = nx1;
;             if (tid < 256) rsd[(slot ^ 1) * 256 + tid] = fast_rsq(nrs * (1.0f / DM) + EPS);
;         }
	v_pk_fma_f32 v[28:29], v[20:21], v[88:89], v[28:29]
	v_pk_fma_f32 v[34:35], v[22:23], v[94:95], v[34:35]
	v_pk_fma_f32 v[20:21], v[20:21], v[84:85], v[96:97]
	v_mul_f32_e32 v36, 0xbfb8aa3b, v34
	v_exp_f32_e32 v38, v36
	v_mul_f32_e32 v36, 0xbfb8aa3b, v35
	v_exp_f32_e32 v39, v36
	v_pk_fma_f32 v[28:29], v[12:13], v[92:93], v[28:29]
	v_pk_mul_f32 v[4:5], v[4:5], v[44:45]
	v_pk_fma_f32 v[12:13], v[12:13], v[88:89], v[20:21]
	v_pk_fma_f32 v[36:37], v[64:65], v[48:49], v[80:81]
	v_add_f32_e32 v38, 1.0, v38
	v_add_f32_e32 v39, 1.0, v39
	v_pk_fma_f32 v[4:5], v[4:5], v[92:93], v[12:13]
	v_pk_mul_f32 v[16:17], v[16:17], v[50:51]
	v_rcp_f32_e32 v38, v38
	v_rcp_f32_e32 v39, v39
	v_pk_fma_f32 v[36:37], v[24:25], v[68:69], v[36:37]
	v_mul_f32_e32 v12, 0xbfb8aa3b, v4
	v_mul_f32_e32 v13, 0xbfb8aa3b, v5
	v_pk_fma_f32 v[36:37], v[16:17], v[76:77], v[36:37]
	v_exp_f32_e32 v12, v12
	v_exp_f32_e32 v13, v13
	v_pk_mul_f32 v[32:33], v[36:37], v[32:33]
	v_pk_fma_f32 v[36:37], v[66:67], v[40:41], v[82:83]
	v_pk_mul_f32 v[18:19], v[18:19], v[72:73]
	v_pk_fma_f32 v[36:37], v[26:27], v[70:71], v[36:37]
	v_pk_mul_f32 v[34:35], v[34:35], v[38:39]
	v_pk_fma_f32 v[36:37], v[18:19], v[78:79], v[36:37]
	v_add_f32_e32 v12, 1.0, v12
	v_pk_mul_f32 v[34:35], v[36:37], v[34:35]
	v_add_f32_e32 v13, 1.0, v13
	v_cvt_pk_bf16_f32 v32, v32, v33
	v_cvt_pk_bf16_f32 v33, v34, v35
	v_lshl_add_u64 v[34:35], v[124:125], 0, v[56:57]
	v_rcp_f32_e32 v12, v12
	v_rcp_f32_e32 v13, v13
	global_store_dwordx2 v[34:35], v[32:33], off
	v_mul_f32_e32 v33, 0xbfb8aa3b, v28
	v_exp_f32_e32 v34, v33
	v_mul_f32_e32 v33, 0xbfb8aa3b, v29
	v_mov_b32_e32 v32, v74
	v_exp_f32_e32 v35, v33
	v_mov_b32_e32 v33, v74
	v_pk_mul_f32 v[14:15], v[14:15], v[32:33]
	v_mov_b32_e32 v74, v75
	v_pk_mul_f32 v[4:5], v[4:5], v[12:13]
	v_pk_fma_f32 v[12:13], v[22:23], v[86:87], v[98:99]
	v_pk_mul_f32 v[6:7], v[6:7], v[74:75]
	v_pk_fma_f32 v[12:13], v[14:15], v[90:91], v[12:13]
	v_pk_fma_f32 v[30:31], v[30:31], v[86:87], v[98:99]
	v_pk_fma_f32 v[6:7], v[6:7], v[94:95], v[12:13]
	v_pk_fma_f32 v[30:31], v[22:23], v[90:91], v[30:31]
	v_mul_f32_e32 v12, 0xbfb8aa3b, v6
	v_pk_fma_f32 v[30:31], v[14:15], v[94:95], v[30:31]
	v_exp_f32_e32 v14, v12
	v_mul_f32_e32 v12, 0xbfb8aa3b, v7
	v_exp_f32_e32 v15, v12
	v_pk_mul_f32 v[10:11], v[10:11], v[32:33]
	v_mul_f32_e32 v32, 0xbfb8aa3b, v30
	v_mul_f32_e32 v33, 0xbfb8aa3b, v31
	v_exp_f32_e32 v32, v32
	v_exp_f32_e32 v33, v33
	v_add_f32_e32 v14, 1.0, v14
	v_add_f32_e32 v15, 1.0, v15
	v_add_f32_e32 v34, 1.0, v34
	v_add_f32_e32 v35, 1.0, v35
	v_pk_fma_f32 v[24:25], v[24:25], v[64:65], v[80:81]
	v_rcp_f32_e32 v14, v14
	v_rcp_f32_e32 v15, v15
	v_rcp_f32_e32 v34, v34
	v_rcp_f32_e32 v35, v35
	v_pk_mul_f32 v[8:9], v[8:9], v[46:47]
	v_add_f32_e32 v32, 1.0, v32
	v_add_f32_e32 v33, 1.0, v33
	v_pk_fma_f32 v[24:25], v[16:17], v[68:69], v[24:25]
	v_pk_fma_f32 v[12:13], v[16:17], v[64:65], v[80:81]
	v_rcp_f32_e32 v32, v32
	v_rcp_f32_e32 v33, v33
	v_pk_fma_f32 v[24:25], v[8:9], v[76:77], v[24:25]
	v_pk_mul_f32 v[0:1], v[0:1], v[44:45]
	v_pk_fma_f32 v[8:9], v[8:9], v[68:69], v[12:13]
	v_pk_fma_f32 v[26:27], v[26:27], v[66:67], v[82:83]
	v_pk_fma_f32 v[0:1], v[0:1], v[76:77], v[8:9]
	v_pk_mul_f32 v[28:29], v[28:29], v[34:35]
	v_pk_mul_f32 v[0:1], v[0:1], v[4:5]
	v_pk_mul_f32 v[4:5], v[6:7], v[14:15]
	v_pk_fma_f32 v[6:7], v[18:19], v[66:67], v[82:83]
	v_pk_fma_f32 v[26:27], v[18:19], v[70:71], v[26:27]
	v_pk_mul_f32 v[2:3], v[2:3], v[74:75]
	v_pk_fma_f32 v[6:7], v[10:11], v[70:71], v[6:7]
	v_pk_mul_f32 v[24:25], v[24:25], v[28:29]
	v_pk_mul_f32 v[28:29], v[30:31], v[32:33]
	v_pk_fma_f32 v[26:27], v[10:11], v[78:79], v[26:27]
	v_pk_fma_f32 v[2:3], v[2:3], v[78:79], v[6:7]
	v_pk_mul_f32 v[26:27], v[26:27], v[28:29]
	v_pk_mul_f32 v[2:3], v[2:3], v[4:5]
	v_cvt_pk_bf16_f32 v24, v24, v25
	v_cvt_pk_bf16_f32 v25, v26, v27
	v_lshl_add_u64 v[26:27], v[130:131], 0, v[56:57]
	v_cvt_pk_bf16_f32 v0, v0, v1
	v_cvt_pk_bf16_f32 v1, v2, v3
	v_lshl_add_u64 v[2:3], v[134:135], 0, v[56:57]
	global_store_dwordx2 v[26:27], v[24:25], off
	global_store_dwordx2 v[2:3], v[0:1], off
	s_and_b64 vcc, exec, s[10:11]
	s_mov_b64 s[0:1], -1
	s_cbranch_vccnz .LBB0_681
	s_xor_b32 s4, s35, 0x400
	v_lshlrev_b32_e32 v0, 2, v226
	v_lshl_add_u32 v0, s4, 2, v0
	v_add_u32_e32 v0, 0x22040, v0
	v_cmp_gt_i32_e32 vcc, s65, v226
	s_waitcnt vmcnt(16)
	ds_write2st64_b32 v0, v228, v227 offset1:8
	s_and_saveexec_b64 s[0:1], vcc
	s_cbranch_execz .LBB0_728
	v_ffbh_u32_e32 v4, v253
	v_min_u32_e32 v4, 32, v4
	v_lshlrev_b64 v[2:3], v4, v[252:253]
	v_min_u32_e32 v2, 1, v2
	v_or_b32_e32 v2, v3, v2
	v_cvt_f32_u32_e32 v2, v2
	v_sub_u32_e32 v3, 32, v4
	v_ldexp_f32 v2, v2, v3
	v_mul_f32_e32 v2, 0x33800000, v2
	v_fmamk_f32 v229, v2, 0x3a800000, v223
	v_rsq_f32_e32 v0, v229
	v_lshl_add_u32 v1, v226, 2, s4
	v_add_u32_e32 v1, 0x24040, v1
	ds_write_b32 v1, v0

; __device__ __forceinline__ float rsq_sum(const u64_t* rsq, int row) { return (float)rsq[row] * (1.0f / 16777216.0f); }
; __device__ __forceinline__ float row_rstd(const u64_t* rsq, int row) { return fast_rsq(rsq_sum(rsq, row) * (1.0f / DM) + EPS); }
; #define PG8_EPI_BAR() do { asm volatile("s_waitcnt lgkmcnt(0)" ::: "memory"); __builtin_amdgcn_s_barrier(); asm volatile("" ::: "memory"); } while (0)
;     __device__ __forceinline__ void run(const f32x4 (&acc)[2][2][4][2], const Unit& u, const Unit& nxt, bool has_next, int ui, int wr, int wc, int fr_in, int fq_in) const {
;         int fr = fr_in, fq = fq_in; asm volatile("" : "+v"(fr), "+v"(fq));
;         const int tid = (wr * 4 + wc) * 64 + fq * 16 + fr;
;         const int slot = ui & 1;
;         if (ui == 0) {
;             prm[slot * 1024 + tid] = ldp(tid, u.pn); prm[slot * 1024 + tid + 512] = ldp(tid + 512, u.pn);
;             if (tid < 256) rsd[slot * 256 + tid] = row_rstd(rsq, u.pm * BM + tid);
;             PG8_EPI_BAR();
;         }
;         float nx0 = 0.f, nx1 = 0.f, nrs = 1.f;
;         if (has_next) { nx0 = ldp(tid, nxt.pn); nx1 = ldp(tid + 512, nxt.pn); if (tid < 256) nrs = rsq_sum(rsq, nxt.pm * BM + tid); }
.LBB0_1552:
	v_bfe_u32 v73, v226, 7, 2
	v_ashrrev_i32_e32 v72, 9, v226
	v_and_b32_e32 v74, 0x7f, v226
	v_mul_u32_u24_e32 v75, 0x1600, v73
	v_cmp_eq_u32_e32 vcc, 3, v73
	v_add_u32_e32 v102, 0x200, v226
	v_mul_i32_i24_e32 v72, 0xb00, v72
	v_cndmask_b32_e64 v100, v75, 0, vcc
	v_lshl_or_b32 v101, s28, 7, v74
	v_mov_b32_e32 v73, s53
	v_mov_b32_e32 v74, s55
	v_ashrrev_i32_e32 v102, 9, v102
	v_add3_u32 v72, v101, v72, v100
	v_cndmask_b32_e32 v75, v73, v74, vcc
	v_mov_b32_e32 v73, s52
	v_mov_b32_e32 v74, s54
	v_mul_i32_i24_e32 v102, 0xb00, v102
	v_cndmask_b32_e32 v74, v73, v74, vcc
	v_ashrrev_i32_e32 v73, 31, v72
	v_add3_u32 v100, v102, v101, v100
	v_lshl_add_u64 v[72:73], v[72:73], 2, v[74:75]
	v_ashrrev_i32_e32 v101, 31, v100
	v_lshl_add_u64 v[74:75], v[100:101], 2, v[74:75]
	global_load_dword v228, v[72:73], off
	global_load_dword v227, v[74:75], off
	v_cmp_gt_i32_e32 vcc, s33, v226
	v_mov_b32_e32 v229, 0x3a80218e
	s_and_saveexec_b64 s[0:1], vcc
	s_cbranch_execz .LBB0_1554
	v_lshl_add_u32 v72, s30, 8, v226
	v_ashrrev_i32_e32 v73, 31, v72
	v_lshl_add_u64 v[72:73], v[72:73], 3, s[18:19]
	global_load_dwordx2 v[252:253], v[72:73], off

; __device__ __forceinline__ unsigned pk2(float lo, float hi) { f32x2_t v = {lo, hi}; bf16x2_t b = __builtin_convertvector(v, bf16x2_t); return __builtin_bit_cast(unsigned, b); }
; __device__ __forceinline__ float sigmoidf_(float v) { return fast_rcp(1.0f + fast_exp2(-v * LOG2E)); }
;     __device__ __forceinline__ void run(const f32x4 (&acc)[2][2][4][2], const Unit& u, const Unit& nxt, bool has_next, int ui, int wr, int wc, int fr_in, int fq_in) const {
;     ...
;             for (int ai = 0; ai < 2; ++ai) {
;                 const int grp = 2 * ai + wr;
;                 f32x4 hg2 = {0.f, 0.f, 0.f, 0.f}, hg3 = hg2, hv2 = hg2, hv3 = hg2;
;                 if (grp > 0 && fr == 0) { const PG8_LAS float* xp = xr + ((grp - 1) * 2) * 256 + cl;
;                     hg2 = *(const PG8_LAS f32x4*)(xp); hg3 = *(const PG8_LAS f32x4*)(xp + 256); hv2 = *(const PG8_LAS f32x4*)(xp + 128); hv3 = *(const PG8_LAS f32x4*)(xp + 256 + 128); }
;                 f32x4 pg2, pg1, pv2, pv1;
;                 {
;                     const f32x4 g2 = acc[ai][0][2][n] * rs[ai][2], g3 = acc[ai][0][3][n] * rs[ai][3], v2 = acc[ai][1][2][n] * rs[ai][2], v3 = acc[ai][1][3][n] * rs[ai][3];
; #pragma unroll
;                     for (int i = 0; i < 4; ++i) {
;                         float a0 = g2[i], a1 = g3[i], a2 = v2[i], a3 = v3[i];
;                         asm volatile("" : "+v"(a0), "+v"(a1), "+v"(a2), "+v"(a3));
;                         const float t0 = DPPF(a0, 0x111), t1 = DPPF(a1, 0x111), t2 = DPPF(a2, 0x111), t3 = DPPF(a3, 0x111);
;                         pg2[i] = t0 + hg2[i]; pg1[i] = t1 + hg3[i]; pv2[i] = t2 + hv2[i]; pv1[i] = t3 + hv3[i]; }
;                 }
; #pragma unroll
;                 for (int m = 0; m < 4; ++m) {
;                     const f32x4 gc = acc[ai][0][m][n] * rs[ai][m], vc = acc[ai][1][m][n] * rs[ai][m];
;                     const f32x4 cgt = bg + wg0 * pg2 + wg1 * pg1 + wg2 * gc, cvl = bv + wv0 * pv2 + wv1 * pv1 + wv2 * vc;
;                     float a[4];
; #pragma unroll
;                     for (int i = 0; i < 4; ++i) a[i] = cgt[i] * sigmoidf_(cgt[i]) * cvl[i];
;                     u32x2 w; w.x = pk2(a[0], a[1]); w.y = pk2(a[2], a[3]);
;                     *(u32x2*)(A + (size_t)(u.pm * BM + ai * 128 + wr * 64 + 4 * fr + m) * DFF + ch) = w;
;                     pg2 = pg1; pg1 = gc; pv2 = pv1; pv1 = vc;
;                 }
.LBB0_1587:
	s_or_b64 exec, exec, s[0:1]
	v_mul_f32_e32 v53, v12, v74
	v_mul_f32_e32 v55, v4, v75
	v_mul_f32_e32 v59, v8, v74
	v_mul_f32_e32 v61, v0, v75
	v_mov_b32_e32 v54, 0
	v_mov_b32_e32 v58, 0
	v_mov_b32_e32 v60, 0
	v_mov_b32_e32 v52, 0
	v_mov_b32_dpp v54, v55 row_shr:1 row_mask:0xf bank_mask:0xf
	v_mov_b32_dpp v58, v59 row_shr:1 row_mask:0xf bank_mask:0xf
	v_mov_b32_dpp v60, v61 row_shr:1 row_mask:0xf bank_mask:0xf
	v_mul_f32_e32 v55, v13, v74
	v_mul_f32_e32 v59, v5, v75
	v_mul_f32_e32 v61, v9, v74
	v_mul_f32_e32 v62, v1, v75
	v_mov_b32_dpp v52, v53 row_shr:1 row_mask:0xf bank_mask:0xf
	v_mov_b32_e32 v53, 0
	v_mov_b32_e32 v48, v72
	v_mov_b32_e32 v49, v72
	v_mov_b32_dpp v53, v55 row_shr:1 row_mask:0xf bank_mask:0xf
	v_mov_b32_e32 v55, 0
	s_waitcnt lgkmcnt(0)
	v_pk_add_f32 v[40:41], v[40:41], v[52:53]
	v_pk_mul_f32 v[28:29], v[28:29], v[48:49]
	v_mov_b32_dpp v55, v59 row_shr:1 row_mask:0xf bank_mask:0xf
	v_pk_add_f32 v[36:37], v[36:37], v[54:55]
	v_pk_fma_f32 v[40:41], v[84:85], v[40:41], v[96:97]
	v_mov_b32_e32 v59, 0
	v_pk_fma_f32 v[40:41], v[88:89], v[36:37], v[40:41]
	v_mul_f32_e32 v63, v14, v74
	v_pk_fma_f32 v[40:41], v[28:29], v[92:93], v[40:41]
	v_mul_f32_e32 v101, v6, v75
	v_mul_f32_e32 v103, v10, v74
	v_mul_f32_e32 v109, v2, v75
	v_mul_f32_e32 v52, 0xbfb8aa3b, v40
	v_mul_f32_e32 v53, 0xbfb8aa3b, v41
	v_mov_b32_dpp v59, v61 row_shr:1 row_mask:0xf bank_mask:0xf
	v_mov_b32_e32 v61, 0
	v_mov_b32_e32 v100, 0
	v_mov_b32_e32 v102, 0
	v_mov_b32_e32 v108, 0
	v_exp_f32_e32 v52, v52
	v_exp_f32_e32 v53, v53
	v_mov_b32_dpp v61, v62 row_shr:1 row_mask:0xf bank_mask:0xf
	v_mov_b32_e32 v62, 0
	v_mov_b32_dpp v100, v101 row_shr:1 row_mask:0xf bank_mask:0xf
	v_mov_b32_dpp v102, v103 row_shr:1 row_mask:0xf bank_mask:0xf
	v_mov_b32_dpp v108, v109 row_shr:1 row_mask:0xf bank_mask:0xf
	v_mul_f32_e32 v101, v15, v74
	v_mul_f32_e32 v103, v7, v75
	v_mul_f32_e32 v109, v11, v74
	v_mul_f32_e32 v110, v3, v75
	v_mov_b32_dpp v62, v63 row_shr:1 row_mask:0xf bank_mask:0xf
	v_mov_b32_e32 v63, 0
	v_add_f32_e32 v52, 1.0, v52
	v_add_f32_e32 v53, 1.0, v53
	v_mov_b32_dpp v63, v101 row_shr:1 row_mask:0xf bank_mask:0xf
	v_mov_b32_e32 v101, 0
	v_rcp_f32_e32 v52, v52
	v_rcp_f32_e32 v53, v53
	v_mov_b32_dpp v101, v103 row_shr:1 row_mask:0xf bank_mask:0xf
	v_mov_b32_e32 v103, 0
	v_pk_add_f32 v[42:43], v[42:43], v[62:63]
	v_mov_b32_e32 v111, v72
	v_mov_b32_dpp v103, v109 row_shr:1 row_mask:0xf bank_mask:0xf
	v_mov_b32_e32 v109, 0
	v_pk_add_f32 v[38:39], v[38:39], v[100:101]
	v_pk_fma_f32 v[42:43], v[86:87], v[42:43], v[98:99]
	v_mov_b32_dpp v109, v110 row_shr:1 row_mask:0xf bank_mask:0xf
	v_mov_b32_e32 v110, v72
	v_pk_mul_f32 v[30:31], v[30:31], v[110:111]
	v_pk_fma_f32 v[42:43], v[90:91], v[38:39], v[42:43]
	v_pk_mul_f32 v[40:41], v[40:41], v[52:53]
	v_pk_fma_f32 v[42:43], v[30:31], v[94:95], v[42:43]
	v_pk_add_f32 v[32:33], v[32:33], v[58:59]
	v_mul_f32_e32 v52, 0xbfb8aa3b, v42
	v_mul_f32_e32 v53, 0xbfb8aa3b, v43
	v_exp_f32_e32 v52, v52
	v_exp_f32_e32 v53, v53
	v_pk_mul_f32 v[24:25], v[24:25], v[48:49]
	v_pk_add_f32 v[48:49], v[104:105], v[60:61]
	v_pk_fma_f32 v[32:33], v[64:65], v[32:33], v[80:81]
	v_add_f32_e32 v52, 1.0, v52
	v_add_f32_e32 v53, 1.0, v53
	v_pk_fma_f32 v[32:33], v[68:69], v[48:49], v[32:33]
	v_rcp_f32_e32 v52, v52
	v_rcp_f32_e32 v53, v53
	v_pk_fma_f32 v[32:33], v[24:25], v[76:77], v[32:33]
	v_pk_add_f32 v[34:35], v[34:35], v[102:103]
	v_pk_mul_f32 v[32:33], v[32:33], v[40:41]
	v_pk_add_f32 v[40:41], v[106:107], v[108:109]
	v_pk_fma_f32 v[34:35], v[66:67], v[34:35], v[82:83]
	v_pk_mul_f32 v[26:27], v[26:27], v[110:111]
	v_pk_fma_f32 v[34:35], v[70:71], v[40:41], v[34:35]
	v_pk_mul_f32 v[42:43], v[42:43], v[52:53]
	v_pk_fma_f32 v[34:35], v[26:27], v[78:79], v[34:35]
	v_cvt_pk_bf16_f32 v32, v32, v33
	v_pk_mul_f32 v[34:35], v[34:35], v[42:43]
	v_mov_b32_e32 v50, v73
	v_cvt_pk_bf16_f32 v33, v34, v35
	v_lshl_add_u64 v[34:35], v[122:123], 0, v[56:57]
	v_mov_b32_e32 v51, v73
	global_store_dwordx2 v[34:35], v[32:33], off
	v_pk_fma_f32 v[32:33], v[84:85], v[36:37], v[96:97]
	v_pk_mul_f32 v[20:21], v[20:21], v[50:51]
	v_pk_fma_f32 v[32:33], v[28:29], v[88:89], v[32:33]
	v_mov_b32_e32 v72, v73
	v_pk_fma_f32 v[32:33], v[20:21], v[92:93], v[32:33]
	v_pk_mul_f32 v[22:23], v[22:23], v[72:73]
	v_mul_f32_e32 v34, 0xbfb8aa3b, v32
	v_mul_f32_e32 v35, 0xbfb8aa3b, v33
	v_exp_f32_e32 v34, v34
	v_exp_f32_e32 v35, v35
	v_mov_b32_e32 v46, v74
	v_mov_b32_e32 v47, v74
	v_add_f32_e32 v34, 1.0, v34
	v_add_f32_e32 v35, 1.0, v35
	v_rcp_f32_e32 v34, v34
	v_rcp_f32_e32 v35, v35
	v_pk_fma_f32 v[28:29], v[28:29], v[84:85], v[96:97]
	v_mov_b32_e32 v44, v75
	v_mov_b32_e32 v45, v75
	v_pk_mul_f32 v[32:33], v[32:33], v[34:35]
	v_pk_fma_f32 v[34:35], v[86:87], v[38:39], v[98:99]
	v_pk_mul_f32 v[12:13], v[12:13], v[46:47]
	v_pk_fma_f32 v[34:35], v[30:31], v[90:91], v[34:35]
; __device__ __forceinline__ unsigned pk2(float lo, float hi) { f32x2_t v = {lo, hi}; bf16x2_t b = __builtin_convertvector(v, bf16x2_t); return __builtin_bit_cast(unsigned, b); }
; __device__ __forceinline__ float fast_rsq(float x) { return __builtin_amdgcn_rsqf(x); }
;     __device__ __forceinline__ void run(const f32x4 (&acc)[2][2][4][2], const Unit& u, const Unit& nxt, bool has_next, int ui, int wr, int wc, int fr_in, int fq_in) const {
;     ...
;                     u32x2 w; w.x = pk2(a[0], a[1]); w.y = pk2(a[2], a[3]);
;                     *(u32x2*)(A + (size_t)(u.pm * BM + ai * 128 + wr * 64 + 4 * fr + m) * DFF + ch) = w;
;                     pg2 = pg1; pg1 = gc; pv2 = pv1; pv1 = vc;
;                 }
;                 asm volatile("" ::: "memory");
;             }
;         }
;         if (has_next) {
;             prm[(slot ^ 1) * 1024 + tid] = nx0; prm[(slot ^ 1) * 1024 + tid + 512] = nx1;
;             if (tid < 256) rsd[(slot ^ 1) * 256 + tid] = fast_rsq(nrs * (1.0f / DM) + EPS);
;         }
	v_pk_fma_f32 v[28:29], v[20:21], v[88:89], v[28:29]
	v_pk_fma_f32 v[34:35], v[22:23], v[94:95], v[34:35]
	v_pk_fma_f32 v[20:21], v[20:21], v[84:85], v[96:97]
	v_mul_f32_e32 v36, 0xbfb8aa3b, v34
	v_exp_f32_e32 v38, v36
	v_mul_f32_e32 v36, 0xbfb8aa3b, v35
	v_exp_f32_e32 v39, v36
	v_pk_fma_f32 v[28:29], v[12:13], v[92:93], v[28:29]
	v_pk_mul_f32 v[4:5], v[4:5], v[44:45]
	v_pk_fma_f32 v[12:13], v[12:13], v[88:89], v[20:21]
	v_pk_fma_f32 v[36:37], v[64:65], v[48:49], v[80:81]
	v_add_f32_e32 v38, 1.0, v38
	v_add_f32_e32 v39, 1.0, v39
	v_pk_fma_f32 v[4:5], v[4:5], v[92:93], v[12:13]
	v_pk_mul_f32 v[16:17], v[16:17], v[50:51]
	v_rcp_f32_e32 v38, v38
	v_rcp_f32_e32 v39, v39
	v_pk_fma_f32 v[36:37], v[24:25], v[68:69], v[36:37]
	v_mul_f32_e32 v12, 0xbfb8aa3b, v4
	v_mul_f32_e32 v13, 0xbfb8aa3b, v5
	v_pk_fma_f32 v[36:37], v[16:17], v[76:77], v[36:37]
	v_exp_f32_e32 v12, v12
	v_exp_f32_e32 v13, v13
	v_pk_mul_f32 v[32:33], v[36:37], v[32:33]
	v_pk_fma_f32 v[36:37], v[66:67], v[40:41], v[82:83]
	v_pk_mul_f32 v[18:19], v[18:19], v[72:73]
	v_pk_fma_f32 v[36:37], v[26:27], v[70:71], v[36:37]
	v_pk_mul_f32 v[34:35], v[34:35], v[38:39]
	v_pk_fma_f32 v[36:37], v[18:19], v[78:79], v[36:37]
	v_add_f32_e32 v12, 1.0, v12
	v_pk_mul_f32 v[34:35], v[36:37], v[34:35]
	v_add_f32_e32 v13, 1.0, v13
	v_cvt_pk_bf16_f32 v32, v32, v33
	v_cvt_pk_bf16_f32 v33, v34, v35
	v_lshl_add_u64 v[34:35], v[124:125], 0, v[56:57]
	v_rcp_f32_e32 v12, v12
	v_rcp_f32_e32 v13, v13
	global_store_dwordx2 v[34:35], v[32:33], off
	v_mul_f32_e32 v33, 0xbfb8aa3b, v28
	v_exp_f32_e32 v34, v33
	v_mul_f32_e32 v33, 0xbfb8aa3b, v29
	v_mov_b32_e32 v32, v74
	v_exp_f32_e32 v35, v33
	v_mov_b32_e32 v33, v74
	v_pk_mul_f32 v[14:15], v[14:15], v[32:33]
	v_mov_b32_e32 v74, v75
	v_pk_mul_f32 v[4:5], v[4:5], v[12:13]
	v_pk_fma_f32 v[12:13], v[22:23], v[86:87], v[98:99]
	v_pk_mul_f32 v[6:7], v[6:7], v[74:75]
	v_pk_fma_f32 v[12:13], v[14:15], v[90:91], v[12:13]
	v_pk_fma_f32 v[30:31], v[30:31], v[86:87], v[98:99]
	v_pk_fma_f32 v[6:7], v[6:7], v[94:95], v[12:13]
	v_pk_fma_f32 v[30:31], v[22:23], v[90:91], v[30:31]
	v_mul_f32_e32 v12, 0xbfb8aa3b, v6
	v_pk_fma_f32 v[30:31], v[14:15], v[94:95], v[30:31]
	v_exp_f32_e32 v14, v12
	v_mul_f32_e32 v12, 0xbfb8aa3b, v7
	v_exp_f32_e32 v15, v12
	v_pk_mul_f32 v[10:11], v[10:11], v[32:33]
	v_mul_f32_e32 v32, 0xbfb8aa3b, v30
	v_mul_f32_e32 v33, 0xbfb8aa3b, v31
	v_exp_f32_e32 v32, v32
	v_exp_f32_e32 v33, v33
	v_add_f32_e32 v14, 1.0, v14
	v_add_f32_e32 v15, 1.0, v15
	v_add_f32_e32 v34, 1.0, v34
	v_add_f32_e32 v35, 1.0, v35
	v_pk_fma_f32 v[24:25], v[24:25], v[64:65], v[80:81]
	v_rcp_f32_e32 v14, v14
	v_rcp_f32_e32 v15, v15
	v_rcp_f32_e32 v34, v34
	v_rcp_f32_e32 v35, v35
	v_pk_mul_f32 v[8:9], v[8:9], v[46:47]
	v_add_f32_e32 v32, 1.0, v32
	v_add_f32_e32 v33, 1.0, v33
	v_pk_fma_f32 v[24:25], v[16:17], v[68:69], v[24:25]
	v_pk_fma_f32 v[12:13], v[16:17], v[64:65], v[80:81]
	v_rcp_f32_e32 v32, v32
	v_rcp_f32_e32 v33, v33
	v_pk_fma_f32 v[24:25], v[8:9], v[76:77], v[24:25]
	v_pk_mul_f32 v[0:1], v[0:1], v[44:45]
	v_pk_fma_f32 v[8:9], v[8:9], v[68:69], v[12:13]
	v_pk_fma_f32 v[26:27], v[26:27], v[66:67], v[82:83]
	v_pk_fma_f32 v[0:1], v[0:1], v[76:77], v[8:9]
	v_pk_mul_f32 v[28:29], v[28:29], v[34:35]
	v_pk_mul_f32 v[0:1], v[0:1], v[4:5]
	v_pk_mul_f32 v[4:5], v[6:7], v[14:15]
	v_pk_fma_f32 v[6:7], v[18:19], v[66:67], v[82:83]
	v_pk_fma_f32 v[26:27], v[18:19], v[70:71], v[26:27]
	v_pk_mul_f32 v[2:3], v[2:3], v[74:75]
	v_pk_fma_f32 v[6:7], v[10:11], v[70:71], v[6:7]
	v_pk_mul_f32 v[24:25], v[24:25], v[28:29]
	v_pk_mul_f32 v[28:29], v[30:31], v[32:33]
	v_pk_fma_f32 v[26:27], v[10:11], v[78:79], v[26:27]
	v_pk_fma_f32 v[2:3], v[2:3], v[78:79], v[6:7]
	v_pk_mul_f32 v[26:27], v[26:27], v[28:29]
	v_pk_mul_f32 v[2:3], v[2:3], v[4:5]
	v_cvt_pk_bf16_f32 v24, v24, v25
	v_cvt_pk_bf16_f32 v25, v26, v27
	v_lshl_add_u64 v[26:27], v[130:131], 0, v[56:57]
	v_cvt_pk_bf16_f32 v0, v0, v1
	v_cvt_pk_bf16_f32 v1, v2, v3
	v_lshl_add_u64 v[2:3], v[134:135], 0, v[56:57]
	global_store_dwordx2 v[26:27], v[24:25], off
	global_store_dwordx2 v[2:3], v[0:1], off
	s_and_b64 vcc, exec, s[6:7]
	s_mov_b64 s[0:1], -1
	s_cbranch_vccnz .LBB0_1543
	s_xor_b32 s4, s29, 0x400
	v_lshlrev_b32_e32 v0, 2, v226
	v_lshl_add_u32 v0, s4, 2, v0
	v_add_u32_e32 v0, 0x22040, v0
	v_cmp_gt_i32_e32 vcc, s33, v226
	s_waitcnt vmcnt(16)
	ds_write2st64_b32 v0, v228, v227 offset1:8
	s_and_saveexec_b64 s[0:1], vcc
	s_cbranch_execz .LBB0_1590
	v_ffbh_u32_e32 v4, v253
	v_min_u32_e32 v4, 32, v4
	v_lshlrev_b64 v[2:3], v4, v[252:253]
	v_min_u32_e32 v2, 1, v2
	v_or_b32_e32 v2, v3, v2
	v_cvt_f32_u32_e32 v2, v2
	v_sub_u32_e32 v3, 32, v4
	v_ldexp_f32 v2, v2, v3
	v_mul_f32_e32 v2, 0x33800000, v2
	v_fmamk_f32 v229, v2, 0x3a800000, v223
	v_rsq_f32_e32 v0, v229
	v_lshl_add_u32 v1, v226, 2, s4
	v_add_u32_e32 v1, 0x24040, v1
	ds_write_b32 v1, v0

; __global__ void __launch_bounds__(512, 2) fwd_megakernel(Args a) {
	.amdhsa_kernel _Z14fwd_megakernel4Args
		.amdhsa_group_segment_fixed_size 149760
		.amdhsa_private_segment_fixed_size 0
		.amdhsa_kernarg_size 416
		.amdhsa_user_sgpr_count 2
		.amdhsa_user_sgpr_dispatch_ptr 0
		.amdhsa_user_sgpr_queue_ptr 0
		.amdhsa_user_sgpr_kernarg_segment_ptr 1
		.amdhsa_user_sgpr_dispatch_id 0
		.amdhsa_user_sgpr_kernarg_preload_length 0
		.amdhsa_user_sgpr_kernarg_preload_offset 0
		.amdhsa_user_sgpr_private_segment_size 0
		.amdhsa_uses_dynamic_stack 0
		.amdhsa_enable_private_segment 0
		.amdhsa_system_sgpr_workgroup_id_x 1
		.amdhsa_system_sgpr_workgroup_id_y 0
		.amdhsa_system_sgpr_workgroup_id_z 0
		.amdhsa_system_sgpr_workgroup_info 0
		.amdhsa_system_vgpr_workitem_id 2
		.amdhsa_next_free_vgpr 256
		.amdhsa_next_free_sgpr 102
		.amdhsa_accum_offset 256
		.amdhsa_reserve_vcc 1
		.amdhsa_float_round_mode_32 0
		.amdhsa_float_round_mode_16_64 0
		.amdhsa_float_denorm_mode_32 3
		.amdhsa_float_denorm_mode_16_64 3
		.amdhsa_dx10_clamp 1
		.amdhsa_ieee_mode 1
		.amdhsa_fp16_overflow 0
		.amdhsa_tg_split 0
		.amdhsa_exception_fp_ieee_invalid_op 0
		.amdhsa_exception_fp_denorm_src 0
		.amdhsa_exception_fp_ieee_div_zero 0
		.amdhsa_exception_fp_ieee_overflow 0
		.amdhsa_exception_fp_ieee_underflow 0
		.amdhsa_exception_fp_ieee_inexact 0
		.amdhsa_exception_int_div_zero 0
	.end_amdhsa_kernel

; __global__ void __launch_bounds__(512, 2) fwd_megakernel(Args a) {
amdhsa.kernels:
  - .agpr_count:     0
    .args:
      - .offset:         0
        .size:           160
        .value_kind:     by_value
      - .offset:         160
        .size:           4
        .value_kind:     hidden_block_count_x
      - .offset:         164
        .size:           4
        .value_kind:     hidden_block_count_y
      - .offset:         168
        .size:           4
        .value_kind:     hidden_block_count_z
      - .offset:         172
        .size:           2
        .value_kind:     hidden_group_size_x
      - .offset:         174
        .size:           2
        .value_kind:     hidden_group_size_y
      - .offset:         176
        .size:           2
        .value_kind:     hidden_group_size_z
      - .offset:         178
        .size:           2
        .value_kind:     hidden_remainder_x
      - .offset:         180
        .size:           2
        .value_kind:     hidden_remainder_y
      - .offset:         182
        .size:           2
        .value_kind:     hidden_remainder_z
      - .offset:         200
        .size:           8
        .value_kind:     hidden_global_offset_x
      - .offset:         208
        .size:           8
        .value_kind:     hidden_global_offset_y
      - .offset:         216
        .size:           8
        .value_kind:     hidden_global_offset_z
      - .offset:         224
        .size:           2
        .value_kind:     hidden_grid_dims
      - .offset:         248
        .size:           8
        .value_kind:     hidden_multigrid_sync_arg
    .group_segment_fixed_size: 149760
    .kernarg_segment_align: 8
    .kernarg_segment_size: 416
    .language:       OpenCL C
    .language_version:
      - 2
      - 0
    .max_flat_workgroup_size: 512
    .name:           _Z14fwd_megakernel4Args
    .private_segment_fixed_size: 0
    .sgpr_count:     108
    .sgpr_spill_count: 61
    .symbol:         _Z14fwd_megakernel4Args.kd
    .uniform_work_group_size: 1
    .uses_dynamic_stack: false
    .vgpr_count:     256
    .vgpr_spill_count: 0
    .wavefront_size: 64
